# GEMM K-loop duplicated: waves 0-3 run it with every s_setprio level raised by one, waves 4-7 unchanged
# baseline (speedup 1.0000x reference)
.LBB0_332:
	s_cmp_lg_u64 s[10:11], 0
	s_cbranch_scc0 .Lgemm_raised
